# opt15
# baseline (speedup 1.0000x reference)
; __device__ __forceinline__ void gemm_phase(const Ctx& cx, const GemmArgs& g_, char* shm) {
;     ...
;             } else if (g.epi == EPI_RES) {
;               const float4 hv = *(const float4*)(g.hin + (size_t)tok * DM + n0);
;               const float h0 = hv.x + a[0], h1 = hv.y + a[1], h2 = hv.z + a[2], h3 = hv.w + a[3];
;               *(float4*)(g.hout + (size_t)tok * DM + n0) = make_float4(h0, h1, h2, h3);
;               if (g.w != nullptr) {
;                 const float4 nw = *(const float4*)(g.w + n0);
;                 uint2 o; o.x = pack2(h0 * nw.x, h1 * nw.y); o.y = pack2(h2 * nw.z, h3 * nw.w);
;                 EMIT_BF16(DM, o);
;                 ssq += h0 * h0 + h1 * h1 + h2 * h2 + h3 * h3;
;               }
.Lmy_fast_res:
	v_or_b32_e32 v194, s4, v168
	v_ashrrev_i32_e32 v195, 31, v194
	v_add_u32_e32 v186, s2, v169
	v_add_u32_e32 v188, v186, v170
	v_ashrrev_i32_e32 v189, 31, v188
	v_add_u32_e32 v186, v186, v0
	v_ashrrev_i32_e32 v187, 31, v186
	v_lshlrev_b64 v[184:185], 12, v[194:195]
	v_lshl_add_u64 v[184:185], s[20:21], 0, v[184:185]
	v_lshl_add_u64 v[184:185], v[188:189], 1, v[184:185]
	v_and_b32_e32 v192, 8, v168
	v_cmp_ne_u32_e32 vcc, 0, v192
	v_mov_b32_e32 v193, 0xffff8040
	s_nop 1
	v_cndmask_b32_e32 v192, 0, v193, vcc
	v_cndmask_b32_e64 v193, 0, -1, vcc
	v_lshl_add_u64 v[184:185], v[184:185], 0, v[192:193]
	v_lshlrev_b64 v[192:193], 13, v[194:195]
	v_lshl_add_u64 v[240:241], s[26:27], 0, v[192:193]
	v_lshl_add_u64 v[242:243], s[28:29], 0, v[192:193]
	v_lshl_add_u64 v[240:241], v[186:187], 2, v[240:241]
	v_lshl_add_u64 v[242:243], v[186:187], 2, v[242:243]
	v_lshl_add_u64 v[244:245], v[186:187], 2, s[30:31]
	v_lshl_add_u64 v[246:247], v[194:195], 2, s[24:25]
	s_mov_b32 s6, 0x8000
	s_mov_b32 s7, 0
	s_mov_b32 s8, 0x10000
	s_mov_b32 s9, 0
	s_mov_b32 s10, 0x80000
	s_mov_b32 s11, 0
	s_mov_b32 s2, 0x20000
	s_mov_b32 s3, 0
	s_mov_b32 s4, 0x100000
	s_mov_b32 s5, 0
	v_mov_b32_e32 v188, v184
	v_mov_b32_e32 v189, v185
	v_lshl_add_u64 v[190:191], v[188:189], 0, s[6:7]
	v_mov_b32_e32 v232, 0
	v_mov_b32_e32 v238, v242
	v_mov_b32_e32 v239, v243
	v_mov_b32_e32 v236, v240
	v_mov_b32_e32 v237, v241
	global_load_dwordx4 v[192:195], v[236:237], off offset:0
	global_load_dwordx4 v[196:199], v[236:237], off offset:64
	global_load_dwordx4 v[200:203], v[236:237], off offset:128
	global_load_dwordx4 v[204:207], v[236:237], off offset:192
	s_and_b64 vcc, exec, s[42:43]
	s_cbranch_vccz .Lmy_res_now_ld_0
	global_load_dwordx4 v[208:211], v[244:245], off offset:0
	global_load_dwordx4 v[212:215], v[244:245], off offset:64
	global_load_dwordx4 v[216:219], v[244:245], off offset:128
	global_load_dwordx4 v[220:223], v[244:245], off offset:192
.Lmy_res_now_ld_0:
	s_and_b64 vcc, exec, s[42:43]
	s_cbranch_vccz .Lmy_res_w0_0
	s_waitcnt vmcnt(0)
	s_branch .Lmy_res_wj_0

; __device__ __forceinline__ void gemm_phase(const Ctx& cx, const GemmArgs& g_, char* shm) {
;     ...
;             } else if (g.epi == EPI_RES) {
;               const float4 hv = *(const float4*)(g.hin + (size_t)tok * DM + n0);
;               const float h0 = hv.x + a[0], h1 = hv.y + a[1], h2 = hv.z + a[2], h3 = hv.w + a[3];
;               *(float4*)(g.hout + (size_t)tok * DM + n0) = make_float4(h0, h1, h2, h3);
;               if (g.w != nullptr) {
;                 const float4 nw = *(const float4*)(g.w + n0);
;                 uint2 o; o.x = pack2(h0 * nw.x, h1 * nw.y); o.y = pack2(h2 * nw.z, h3 * nw.w);
;                 EMIT_BF16(DM, o);
;                 ssq += h0 * h0 + h1 * h1 + h2 * h2 + h3 * h3;
;               }
.Lmy_res_wj_0:
	v_pk_add_f32 v[128:129], v[128:129], v[192:193]
	v_pk_add_f32 v[130:131], v[130:131], v[194:195]
	global_store_dwordx4 v[238:239], v[128:131], off offset:0
	v_pk_add_f32 v[124:125], v[124:125], v[196:197]
	v_pk_add_f32 v[126:127], v[126:127], v[198:199]
	global_store_dwordx4 v[238:239], v[124:127], off offset:64
	v_pk_add_f32 v[120:121], v[120:121], v[200:201]
	v_pk_add_f32 v[122:123], v[122:123], v[202:203]
	global_store_dwordx4 v[238:239], v[120:123], off offset:128
	v_pk_add_f32 v[116:117], v[116:117], v[204:205]
	v_pk_add_f32 v[118:119], v[118:119], v[206:207]
	global_store_dwordx4 v[238:239], v[116:119], off offset:192
	s_and_b64 vcc, exec, s[42:43]
	s_cbranch_vccz .Lmy_res_now_0
	v_pk_mul_f32 v[234:235], v[130:131], v[210:211]
	s_nop 0
	v_cvt_pk_bf16_f32 v225, v234, v235
	v_pk_mul_f32 v[234:235], v[128:129], v[208:209]
	v_pk_mul_f32 v[208:209], v[128:129], v[128:129]
	v_pk_mul_f32 v[210:211], v[130:131], v[130:131]
	v_add_f32_e32 v233, v208, v209
	v_add_f32_e32 v233, v233, v210
	v_cvt_pk_bf16_f32 v224, v234, v235
	v_add_f32_e32 v233, v233, v211
	v_add_f32_e32 v232, v232, v233
	v_pk_mul_f32 v[234:235], v[126:127], v[214:215]
	s_nop 0
	v_cvt_pk_bf16_f32 v227, v234, v235
	v_pk_mul_f32 v[234:235], v[124:125], v[212:213]
	v_pk_mul_f32 v[212:213], v[124:125], v[124:125]
	v_pk_mul_f32 v[214:215], v[126:127], v[126:127]
	v_add_f32_e32 v233, v212, v213
	v_add_f32_e32 v233, v233, v214
	v_cvt_pk_bf16_f32 v226, v234, v235
	v_add_f32_e32 v233, v233, v215
	v_add_f32_e32 v232, v232, v233
	s_nop 1
	v_permlane16_swap_b32_e32 v224, v226
	v_permlane16_swap_b32_e32 v225, v227
	v_pk_mul_f32 v[234:235], v[122:123], v[218:219]
	s_nop 0
	v_cvt_pk_bf16_f32 v229, v234, v235
	v_pk_mul_f32 v[234:235], v[120:121], v[216:217]
	v_pk_mul_f32 v[216:217], v[120:121], v[120:121]
	v_pk_mul_f32 v[218:219], v[122:123], v[122:123]
	v_add_f32_e32 v233, v216, v217
	v_add_f32_e32 v233, v233, v218
	v_cvt_pk_bf16_f32 v228, v234, v235
	v_add_f32_e32 v233, v233, v219
	v_add_f32_e32 v232, v232, v233
	v_pk_mul_f32 v[234:235], v[118:119], v[222:223]
	s_nop 0
	v_cvt_pk_bf16_f32 v231, v234, v235
	v_pk_mul_f32 v[234:235], v[116:117], v[220:221]
	v_pk_mul_f32 v[220:221], v[116:117], v[116:117]
	v_pk_mul_f32 v[222:223], v[118:119], v[118:119]
	v_add_f32_e32 v233, v220, v221
	v_add_f32_e32 v233, v233, v222
	v_cvt_pk_bf16_f32 v230, v234, v235
	v_add_f32_e32 v233, v233, v223
	v_add_f32_e32 v232, v232, v233
	s_nop 1
	v_permlane16_swap_b32_e32 v228, v230
	v_permlane16_swap_b32_e32 v229, v231
	v_mov_b32_e32 v192, v228
	v_mov_b32_e32 v193, v229
	v_mov_b32_e32 v194, v230
	v_mov_b32_e32 v195, v231
	v_mov_b32_dpp v228, v224 row_ror:8 row_mask:0xf bank_mask:0x3
	v_mov_b32_dpp v229, v225 row_ror:8 row_mask:0xf bank_mask:0x3
	v_mov_b32_dpp v230, v226 row_ror:8 row_mask:0xf bank_mask:0x3
	v_mov_b32_dpp v231, v227 row_ror:8 row_mask:0xf bank_mask:0x3
	v_mov_b32_dpp v224, v192 row_ror:8 row_mask:0xf bank_mask:0xc
	v_mov_b32_dpp v225, v193 row_ror:8 row_mask:0xf bank_mask:0xc
	v_mov_b32_dpp v226, v194 row_ror:8 row_mask:0xf bank_mask:0xc
	v_mov_b32_dpp v227, v195 row_ror:8 row_mask:0xf bank_mask:0xc
	global_store_dwordx4 v[188:189], v[224:227], off offset:32
	global_store_dwordx4 v[190:191], v[228:231], off offset:32
	s_nop 1
.Lmy_res_now_0:
	v_mov_b32_e32 v238, v242
	v_mov_b32_e32 v239, v243
	v_mov_b32_e32 v236, v240
	v_mov_b32_e32 v237, v241
	global_load_dwordx4 v[192:195], v[236:237], off offset:512
	global_load_dwordx4 v[196:199], v[236:237], off offset:576
	global_load_dwordx4 v[200:203], v[236:237], off offset:640
	global_load_dwordx4 v[204:207], v[236:237], off offset:704
	s_and_b64 vcc, exec, s[42:43]
	s_cbranch_vccz .Lmy_res_now_ld_1
	global_load_dwordx4 v[208:211], v[244:245], off offset:512
	global_load_dwordx4 v[212:215], v[244:245], off offset:576
	global_load_dwordx4 v[216:219], v[244:245], off offset:640
	global_load_dwordx4 v[220:223], v[244:245], off offset:704

; __device__ __forceinline__ void gemm_phase(const Ctx& cx, const GemmArgs& g_, char* shm) {
;     ...
;             } else if (g.epi == EPI_RES) {
;               const float4 hv = *(const float4*)(g.hin + (size_t)tok * DM + n0);
;               const float h0 = hv.x + a[0], h1 = hv.y + a[1], h2 = hv.z + a[2], h3 = hv.w + a[3];
;               *(float4*)(g.hout + (size_t)tok * DM + n0) = make_float4(h0, h1, h2, h3);
;               if (g.w != nullptr) {
;                 const float4 nw = *(const float4*)(g.w + n0);
;                 uint2 o; o.x = pack2(h0 * nw.x, h1 * nw.y); o.y = pack2(h2 * nw.z, h3 * nw.w);
;                 EMIT_BF16(DM, o);
;                 ssq += h0 * h0 + h1 * h1 + h2 * h2 + h3 * h3;
;               }
.Lmy_res_wj_1:
	v_pk_add_f32 v[112:113], v[112:113], v[192:193]
	v_pk_add_f32 v[114:115], v[114:115], v[194:195]
	global_store_dwordx4 v[238:239], v[112:115], off offset:512
	v_pk_add_f32 v[108:109], v[108:109], v[196:197]
	v_pk_add_f32 v[110:111], v[110:111], v[198:199]
	global_store_dwordx4 v[238:239], v[108:111], off offset:576
	v_pk_add_f32 v[104:105], v[104:105], v[200:201]
	v_pk_add_f32 v[106:107], v[106:107], v[202:203]
	global_store_dwordx4 v[238:239], v[104:107], off offset:640
	v_pk_add_f32 v[100:101], v[100:101], v[204:205]
	v_pk_add_f32 v[102:103], v[102:103], v[206:207]
	global_store_dwordx4 v[238:239], v[100:103], off offset:704
	s_and_b64 vcc, exec, s[42:43]
	s_cbranch_vccz .Lmy_res_now_1
	v_pk_mul_f32 v[234:235], v[114:115], v[210:211]
	s_nop 0
	v_cvt_pk_bf16_f32 v225, v234, v235
	v_pk_mul_f32 v[234:235], v[112:113], v[208:209]
	v_pk_mul_f32 v[208:209], v[112:113], v[112:113]
	v_pk_mul_f32 v[210:211], v[114:115], v[114:115]
	v_add_f32_e32 v233, v208, v209
	v_add_f32_e32 v233, v233, v210
	v_cvt_pk_bf16_f32 v224, v234, v235
	v_add_f32_e32 v233, v233, v211
	v_add_f32_e32 v232, v232, v233
	v_pk_mul_f32 v[234:235], v[110:111], v[214:215]
	s_nop 0
	v_cvt_pk_bf16_f32 v227, v234, v235
	v_pk_mul_f32 v[234:235], v[108:109], v[212:213]
	v_pk_mul_f32 v[212:213], v[108:109], v[108:109]
	v_pk_mul_f32 v[214:215], v[110:111], v[110:111]
	v_add_f32_e32 v233, v212, v213
	v_add_f32_e32 v233, v233, v214
	v_cvt_pk_bf16_f32 v226, v234, v235
	v_add_f32_e32 v233, v233, v215
	v_add_f32_e32 v232, v232, v233
	s_nop 1
	v_permlane16_swap_b32_e32 v224, v226
	v_permlane16_swap_b32_e32 v225, v227
	v_pk_mul_f32 v[234:235], v[106:107], v[218:219]
	s_nop 0
	v_cvt_pk_bf16_f32 v229, v234, v235
	v_pk_mul_f32 v[234:235], v[104:105], v[216:217]
	v_pk_mul_f32 v[216:217], v[104:105], v[104:105]
	v_pk_mul_f32 v[218:219], v[106:107], v[106:107]
	v_add_f32_e32 v233, v216, v217
	v_add_f32_e32 v233, v233, v218
	v_cvt_pk_bf16_f32 v228, v234, v235
	v_add_f32_e32 v233, v233, v219
	v_add_f32_e32 v232, v232, v233
	v_pk_mul_f32 v[234:235], v[102:103], v[222:223]
	s_nop 0
	v_cvt_pk_bf16_f32 v231, v234, v235
	v_pk_mul_f32 v[234:235], v[100:101], v[220:221]
	v_pk_mul_f32 v[220:221], v[100:101], v[100:101]
	v_pk_mul_f32 v[222:223], v[102:103], v[102:103]
	v_add_f32_e32 v233, v220, v221
	v_add_f32_e32 v233, v233, v222
	v_cvt_pk_bf16_f32 v230, v234, v235
	v_add_f32_e32 v233, v233, v223
	v_add_f32_e32 v232, v232, v233
	s_nop 1
	v_permlane16_swap_b32_e32 v228, v230
	v_permlane16_swap_b32_e32 v229, v231
	v_mov_b32_e32 v192, v228
	v_mov_b32_e32 v193, v229
	v_mov_b32_e32 v194, v230
	v_mov_b32_e32 v195, v231
	v_mov_b32_dpp v228, v224 row_ror:8 row_mask:0xf bank_mask:0x3
	v_mov_b32_dpp v229, v225 row_ror:8 row_mask:0xf bank_mask:0x3
	v_mov_b32_dpp v230, v226 row_ror:8 row_mask:0xf bank_mask:0x3
	v_mov_b32_dpp v231, v227 row_ror:8 row_mask:0xf bank_mask:0x3
	v_mov_b32_dpp v224, v192 row_ror:8 row_mask:0xf bank_mask:0xc
	v_mov_b32_dpp v225, v193 row_ror:8 row_mask:0xf bank_mask:0xc
	v_mov_b32_dpp v226, v194 row_ror:8 row_mask:0xf bank_mask:0xc
	v_mov_b32_dpp v227, v195 row_ror:8 row_mask:0xf bank_mask:0xc
	global_store_dwordx4 v[188:189], v[224:227], off offset:288
	global_store_dwordx4 v[190:191], v[228:231], off offset:288
	s_nop 1

; __device__ __forceinline__ void gemm_phase(const Ctx& cx, const GemmArgs& g_, char* shm) {
;     ...
;     for (int bj = 0; bj < 2; ++bj)
; #pragma unroll
;       for (int n = 0; n < 2; ++n) {
;         const int tok = bcol + bj * 128 + wc * 32 + n * 16 + fr;
;         float ssq = 0.f;
;         float rs = 1.f;
;         if ((g.epi == EPI_PROJ || g.epi == EPI_RELU2) && g.gate != nullptr)
;           rs = rsqrtf(((const float*)g.gate)[tok] * (1.0f / DM) + 1e-6f);
; #pragma unroll
;         for (int ai = 0; ai < 2; ++ai) {
;           uint2 pend = make_uint2(0u, 0u);
;     ...
;             } else if (g.epi == EPI_RES) {
;               const float4 hv = *(const float4*)(g.hin + (size_t)tok * DM + n0);
;               const float h0 = hv.x + a[0], h1 = hv.y + a[1], h2 = hv.z + a[2], h3 = hv.w + a[3];
;               *(float4*)(g.hout + (size_t)tok * DM + n0) = make_float4(h0, h1, h2, h3);
;               if (g.w != nullptr) {
;                 const float4 nw = *(const float4*)(g.w + n0);
.Lmy_res_noat_0:
	v_lshl_add_u64 v[188:189], v[184:185], 0, s[8:9]
	v_lshl_add_u64 v[190:191], v[188:189], 0, s[6:7]
	v_mov_b32_e32 v232, 0
	v_lshl_add_u64 v[238:239], v[242:243], 0, s[2:3]
	v_lshl_add_u64 v[236:237], v[240:241], 0, s[2:3]
	global_load_dwordx4 v[192:195], v[236:237], off offset:0
	global_load_dwordx4 v[196:199], v[236:237], off offset:64
	global_load_dwordx4 v[200:203], v[236:237], off offset:128
	global_load_dwordx4 v[204:207], v[236:237], off offset:192
	s_and_b64 vcc, exec, s[42:43]
	s_cbranch_vccz .Lmy_res_now_ld_2
	global_load_dwordx4 v[208:211], v[244:245], off offset:0
	global_load_dwordx4 v[212:215], v[244:245], off offset:64
	global_load_dwordx4 v[216:219], v[244:245], off offset:128
	global_load_dwordx4 v[220:223], v[244:245], off offset:192
.Lmy_res_now_ld_2:
	v_lshl_add_u64 v[236:237], v[240:241], 0, s[2:3]
	global_load_dwordx4 v[100:103], v[236:237], off offset:512
	global_load_dwordx4 v[104:107], v[236:237], off offset:576
	global_load_dwordx4 v[108:111], v[236:237], off offset:640
	global_load_dwordx4 v[112:115], v[236:237], off offset:704
	s_and_b64 vcc, exec, s[42:43]
	s_cbranch_vccz .Lmy_res_now_ld_3
	global_load_dwordx4 v[116:119], v[244:245], off offset:512
	global_load_dwordx4 v[120:123], v[244:245], off offset:576
	global_load_dwordx4 v[124:127], v[244:245], off offset:640
	global_load_dwordx4 v[128:131], v[244:245], off offset:704
.Lmy_res_now_ld_3:
	s_and_b64 vcc, exec, s[42:43]
	s_cbranch_vccz .Lmy_res_w0_2
	s_waitcnt vmcnt(8)
	s_branch .Lmy_res_wj_2

; __device__ __forceinline__ void gemm_phase(const Ctx& cx, const GemmArgs& g_, char* shm) {
;     ...
;             } else if (g.epi == EPI_RES) {
;               const float4 hv = *(const float4*)(g.hin + (size_t)tok * DM + n0);
;               const float h0 = hv.x + a[0], h1 = hv.y + a[1], h2 = hv.z + a[2], h3 = hv.w + a[3];
;               *(float4*)(g.hout + (size_t)tok * DM + n0) = make_float4(h0, h1, h2, h3);
;               if (g.w != nullptr) {
;                 const float4 nw = *(const float4*)(g.w + n0);
;                 uint2 o; o.x = pack2(h0 * nw.x, h1 * nw.y); o.y = pack2(h2 * nw.z, h3 * nw.w);
;                 EMIT_BF16(DM, o);
;                 ssq += h0 * h0 + h1 * h1 + h2 * h2 + h3 * h3;
;               }
.Lmy_res_wj_2:
	v_pk_add_f32 v[96:97], v[96:97], v[192:193]
	v_pk_add_f32 v[98:99], v[98:99], v[194:195]
	global_store_dwordx4 v[238:239], v[96:99], off offset:0
	v_pk_add_f32 v[92:93], v[92:93], v[196:197]
	v_pk_add_f32 v[94:95], v[94:95], v[198:199]
	global_store_dwordx4 v[238:239], v[92:95], off offset:64
	v_pk_add_f32 v[88:89], v[88:89], v[200:201]
	v_pk_add_f32 v[90:91], v[90:91], v[202:203]
	global_store_dwordx4 v[238:239], v[88:91], off offset:128
	v_pk_add_f32 v[84:85], v[84:85], v[204:205]
	v_pk_add_f32 v[86:87], v[86:87], v[206:207]
	global_store_dwordx4 v[238:239], v[84:87], off offset:192
	s_and_b64 vcc, exec, s[42:43]
	s_cbranch_vccz .Lmy_res_now_2
	v_pk_mul_f32 v[234:235], v[98:99], v[210:211]
	s_nop 0
	v_cvt_pk_bf16_f32 v225, v234, v235
	v_pk_mul_f32 v[234:235], v[96:97], v[208:209]
	v_pk_mul_f32 v[208:209], v[96:97], v[96:97]
	v_pk_mul_f32 v[210:211], v[98:99], v[98:99]
	v_add_f32_e32 v233, v208, v209
	v_add_f32_e32 v233, v233, v210
	v_cvt_pk_bf16_f32 v224, v234, v235
	v_add_f32_e32 v233, v233, v211
	v_add_f32_e32 v232, v232, v233
	v_pk_mul_f32 v[234:235], v[94:95], v[214:215]
	s_nop 0
	v_cvt_pk_bf16_f32 v227, v234, v235
	v_pk_mul_f32 v[234:235], v[92:93], v[212:213]
	v_pk_mul_f32 v[212:213], v[92:93], v[92:93]
	v_pk_mul_f32 v[214:215], v[94:95], v[94:95]
	v_add_f32_e32 v233, v212, v213
	v_add_f32_e32 v233, v233, v214
	v_cvt_pk_bf16_f32 v226, v234, v235
	v_add_f32_e32 v233, v233, v215
	v_add_f32_e32 v232, v232, v233
	s_nop 1
	v_permlane16_swap_b32_e32 v224, v226
	v_permlane16_swap_b32_e32 v225, v227
	v_pk_mul_f32 v[234:235], v[90:91], v[218:219]
	s_nop 0
	v_cvt_pk_bf16_f32 v229, v234, v235
	v_pk_mul_f32 v[234:235], v[88:89], v[216:217]
	v_pk_mul_f32 v[216:217], v[88:89], v[88:89]
	v_pk_mul_f32 v[218:219], v[90:91], v[90:91]
	v_add_f32_e32 v233, v216, v217
	v_add_f32_e32 v233, v233, v218
	v_cvt_pk_bf16_f32 v228, v234, v235
	v_add_f32_e32 v233, v233, v219
	v_add_f32_e32 v232, v232, v233
	v_pk_mul_f32 v[234:235], v[86:87], v[222:223]
	s_nop 0
	v_cvt_pk_bf16_f32 v231, v234, v235
	v_pk_mul_f32 v[234:235], v[84:85], v[220:221]
	v_pk_mul_f32 v[220:221], v[84:85], v[84:85]
	v_pk_mul_f32 v[222:223], v[86:87], v[86:87]
	v_add_f32_e32 v233, v220, v221
	v_add_f32_e32 v233, v233, v222
	v_cvt_pk_bf16_f32 v230, v234, v235
	v_add_f32_e32 v233, v233, v223
	v_add_f32_e32 v232, v232, v233
	s_nop 1
	v_permlane16_swap_b32_e32 v228, v230
	v_permlane16_swap_b32_e32 v229, v231
	v_mov_b32_e32 v192, v228
	v_mov_b32_e32 v193, v229
	v_mov_b32_e32 v194, v230
	v_mov_b32_e32 v195, v231
	v_mov_b32_dpp v228, v224 row_ror:8 row_mask:0xf bank_mask:0x3
	v_mov_b32_dpp v229, v225 row_ror:8 row_mask:0xf bank_mask:0x3
	v_mov_b32_dpp v230, v226 row_ror:8 row_mask:0xf bank_mask:0x3
	v_mov_b32_dpp v231, v227 row_ror:8 row_mask:0xf bank_mask:0x3
	v_mov_b32_dpp v224, v192 row_ror:8 row_mask:0xf bank_mask:0xc
	v_mov_b32_dpp v225, v193 row_ror:8 row_mask:0xf bank_mask:0xc
	v_mov_b32_dpp v226, v194 row_ror:8 row_mask:0xf bank_mask:0xc
	v_mov_b32_dpp v227, v195 row_ror:8 row_mask:0xf bank_mask:0xc
	global_store_dwordx4 v[188:189], v[224:227], off offset:32
	global_store_dwordx4 v[190:191], v[228:231], off offset:32
	s_nop 1
.Lmy_res_now_2:
	v_lshl_add_u64 v[238:239], v[242:243], 0, s[2:3]
	v_lshl_add_u64 v[236:237], v[240:241], 0, s[4:5]
	global_load_dwordx4 v[192:195], v[236:237], off offset:0
	global_load_dwordx4 v[196:199], v[236:237], off offset:64
	global_load_dwordx4 v[200:203], v[236:237], off offset:128
	global_load_dwordx4 v[204:207], v[236:237], off offset:192
	s_and_b64 vcc, exec, s[42:43]
	s_cbranch_vccz .Lmy_res_now_ld_4
	global_load_dwordx4 v[208:211], v[244:245], off offset:0
	global_load_dwordx4 v[212:215], v[244:245], off offset:64
	global_load_dwordx4 v[216:219], v[244:245], off offset:128
	global_load_dwordx4 v[220:223], v[244:245], off offset:192
; __device__ __forceinline__ void gemm_phase(const Ctx& cx, const GemmArgs& g_, char* shm) {
;     ...
;             } else if (g.epi == EPI_RES) {
;               const float4 hv = *(const float4*)(g.hin + (size_t)tok * DM + n0);
;               const float h0 = hv.x + a[0], h1 = hv.y + a[1], h2 = hv.z + a[2], h3 = hv.w + a[3];
;               *(float4*)(g.hout + (size_t)tok * DM + n0) = make_float4(h0, h1, h2, h3);
;               if (g.w != nullptr) {
;                 const float4 nw = *(const float4*)(g.w + n0);
;                 uint2 o; o.x = pack2(h0 * nw.x, h1 * nw.y); o.y = pack2(h2 * nw.z, h3 * nw.w);
;                 EMIT_BF16(DM, o);
;                 ssq += h0 * h0 + h1 * h1 + h2 * h2 + h3 * h3;
;               }
.Lmy_res_now_ld_4:
	s_and_b64 vcc, exec, s[42:43]
	s_cbranch_vccz .Lmy_res_w0_3
	s_waitcnt vmcnt(14)
	s_branch .Lmy_res_wj_3
.Lmy_res_w0_3:
	s_waitcnt vmcnt(8)
.Lmy_res_wj_3:
	v_pk_add_f32 v[80:81], v[80:81], v[100:101]
	v_pk_add_f32 v[82:83], v[82:83], v[102:103]
	global_store_dwordx4 v[238:239], v[80:83], off offset:512
	v_pk_add_f32 v[76:77], v[76:77], v[104:105]
	v_pk_add_f32 v[78:79], v[78:79], v[106:107]
	global_store_dwordx4 v[238:239], v[76:79], off offset:576
	v_pk_add_f32 v[72:73], v[72:73], v[108:109]
	v_pk_add_f32 v[74:75], v[74:75], v[110:111]
	global_store_dwordx4 v[238:239], v[72:75], off offset:640
	v_pk_add_f32 v[68:69], v[68:69], v[112:113]
	v_pk_add_f32 v[70:71], v[70:71], v[114:115]
	global_store_dwordx4 v[238:239], v[68:71], off offset:704
	s_and_b64 vcc, exec, s[42:43]
	s_cbranch_vccz .Lmy_res_now_3
	v_pk_mul_f32 v[234:235], v[82:83], v[118:119]
	s_nop 0
	v_cvt_pk_bf16_f32 v225, v234, v235
	v_pk_mul_f32 v[234:235], v[80:81], v[116:117]
	v_pk_mul_f32 v[116:117], v[80:81], v[80:81]
	v_pk_mul_f32 v[118:119], v[82:83], v[82:83]
	v_add_f32_e32 v233, v116, v117
	v_add_f32_e32 v233, v233, v118
	v_cvt_pk_bf16_f32 v224, v234, v235
	v_add_f32_e32 v233, v233, v119
	v_add_f32_e32 v232, v232, v233
	v_pk_mul_f32 v[234:235], v[78:79], v[122:123]
	s_nop 0
	v_cvt_pk_bf16_f32 v227, v234, v235
	v_pk_mul_f32 v[234:235], v[76:77], v[120:121]
	v_pk_mul_f32 v[120:121], v[76:77], v[76:77]
	v_pk_mul_f32 v[122:123], v[78:79], v[78:79]
	v_add_f32_e32 v233, v120, v121
	v_add_f32_e32 v233, v233, v122
	v_cvt_pk_bf16_f32 v226, v234, v235
	v_add_f32_e32 v233, v233, v123
	v_add_f32_e32 v232, v232, v233
	s_nop 1
	v_permlane16_swap_b32_e32 v224, v226
	v_permlane16_swap_b32_e32 v225, v227
	v_pk_mul_f32 v[234:235], v[74:75], v[126:127]
	s_nop 0
	v_cvt_pk_bf16_f32 v229, v234, v235
	v_pk_mul_f32 v[234:235], v[72:73], v[124:125]
	v_pk_mul_f32 v[124:125], v[72:73], v[72:73]
	v_pk_mul_f32 v[126:127], v[74:75], v[74:75]
	v_add_f32_e32 v233, v124, v125
	v_add_f32_e32 v233, v233, v126
	v_cvt_pk_bf16_f32 v228, v234, v235
	v_add_f32_e32 v233, v233, v127
	v_add_f32_e32 v232, v232, v233
	v_pk_mul_f32 v[234:235], v[70:71], v[130:131]
	s_nop 0
	v_cvt_pk_bf16_f32 v231, v234, v235
	v_pk_mul_f32 v[234:235], v[68:69], v[128:129]
	v_pk_mul_f32 v[128:129], v[68:69], v[68:69]
	v_pk_mul_f32 v[130:131], v[70:71], v[70:71]
	v_add_f32_e32 v233, v128, v129
	v_add_f32_e32 v233, v233, v130
	v_cvt_pk_bf16_f32 v230, v234, v235
	v_add_f32_e32 v233, v233, v131
	v_add_f32_e32 v232, v232, v233
	s_nop 1
	v_permlane16_swap_b32_e32 v228, v230
	v_permlane16_swap_b32_e32 v229, v231
	v_mov_b32_e32 v100, v228
	v_mov_b32_e32 v101, v229
	v_mov_b32_e32 v102, v230
	v_mov_b32_e32 v103, v231
	v_mov_b32_dpp v228, v224 row_ror:8 row_mask:0xf bank_mask:0x3
	v_mov_b32_dpp v229, v225 row_ror:8 row_mask:0xf bank_mask:0x3
	v_mov_b32_dpp v230, v226 row_ror:8 row_mask:0xf bank_mask:0x3
	v_mov_b32_dpp v231, v227 row_ror:8 row_mask:0xf bank_mask:0x3
	v_mov_b32_dpp v224, v100 row_ror:8 row_mask:0xf bank_mask:0xc
	v_mov_b32_dpp v225, v101 row_ror:8 row_mask:0xf bank_mask:0xc
	v_mov_b32_dpp v226, v102 row_ror:8 row_mask:0xf bank_mask:0xc
	v_mov_b32_dpp v227, v103 row_ror:8 row_mask:0xf bank_mask:0xc
	global_store_dwordx4 v[188:189], v[224:227], off offset:288
	global_store_dwordx4 v[190:191], v[228:231], off offset:288
	s_nop 1

; __device__ __forceinline__ void gemm_phase(const Ctx& cx, const GemmArgs& g_, char* shm) {
;     ...
;     for (int bj = 0; bj < 2; ++bj)
; #pragma unroll
;       for (int n = 0; n < 2; ++n) {
;         const int tok = bcol + bj * 128 + wc * 32 + n * 16 + fr;
;         float ssq = 0.f;
;         float rs = 1.f;
;         if ((g.epi == EPI_PROJ || g.epi == EPI_RELU2) && g.gate != nullptr)
;           rs = rsqrtf(((const float*)g.gate)[tok] * (1.0f / DM) + 1e-6f);
; #pragma unroll
;         for (int ai = 0; ai < 2; ++ai) {
;           uint2 pend = make_uint2(0u, 0u);
;     ...
;             } else if (g.epi == EPI_RES) {
;               const float4 hv = *(const float4*)(g.hin + (size_t)tok * DM + n0);
;               const float h0 = hv.x + a[0], h1 = hv.y + a[1], h2 = hv.z + a[2], h3 = hv.w + a[3];
;               *(float4*)(g.hout + (size_t)tok * DM + n0) = make_float4(h0, h1, h2, h3);
;               if (g.w != nullptr) {
;                 const float4 nw = *(const float4*)(g.w + n0);
.Lmy_res_noat_1:
	v_lshl_add_u64 v[188:189], v[184:185], 0, s[10:11]
	v_lshl_add_u64 v[190:191], v[188:189], 0, s[6:7]
	v_mov_b32_e32 v232, 0
	v_lshl_add_u64 v[238:239], v[242:243], 0, s[4:5]
	v_lshl_add_u64 v[236:237], v[240:241], 0, s[4:5]
	global_load_dwordx4 v[100:103], v[236:237], off offset:512
	global_load_dwordx4 v[104:107], v[236:237], off offset:576
	global_load_dwordx4 v[108:111], v[236:237], off offset:640
	global_load_dwordx4 v[112:115], v[236:237], off offset:704
	s_and_b64 vcc, exec, s[42:43]
	s_cbranch_vccz .Lmy_res_now_ld_5
	global_load_dwordx4 v[116:119], v[244:245], off offset:512
	global_load_dwordx4 v[120:123], v[244:245], off offset:576
	global_load_dwordx4 v[124:127], v[244:245], off offset:640
	global_load_dwordx4 v[128:131], v[244:245], off offset:704
.Lmy_res_now_ld_5:
	s_and_b64 vcc, exec, s[42:43]
	s_cbranch_vccz .Lmy_res_w0_4
	s_waitcnt vmcnt(15)
	s_branch .Lmy_res_wj_4

; __device__ __forceinline__ void gemm_phase(const Ctx& cx, const GemmArgs& g_, char* shm) {
;     ...
;             } else if (g.epi == EPI_RES) {
;               const float4 hv = *(const float4*)(g.hin + (size_t)tok * DM + n0);
;               const float h0 = hv.x + a[0], h1 = hv.y + a[1], h2 = hv.z + a[2], h3 = hv.w + a[3];
;               *(float4*)(g.hout + (size_t)tok * DM + n0) = make_float4(h0, h1, h2, h3);
;               if (g.w != nullptr) {
;                 const float4 nw = *(const float4*)(g.w + n0);
;                 uint2 o; o.x = pack2(h0 * nw.x, h1 * nw.y); o.y = pack2(h2 * nw.z, h3 * nw.w);
;                 EMIT_BF16(DM, o);
;                 ssq += h0 * h0 + h1 * h1 + h2 * h2 + h3 * h3;
;               }
.Lmy_res_wj_4:
	v_pk_add_f32 v[64:65], v[64:65], v[192:193]
	v_pk_add_f32 v[66:67], v[66:67], v[194:195]
	global_store_dwordx4 v[238:239], v[64:67], off offset:0
	v_pk_add_f32 v[60:61], v[60:61], v[196:197]
	v_pk_add_f32 v[62:63], v[62:63], v[198:199]
	global_store_dwordx4 v[238:239], v[60:63], off offset:64
	v_pk_add_f32 v[56:57], v[56:57], v[200:201]
	v_pk_add_f32 v[58:59], v[58:59], v[202:203]
	global_store_dwordx4 v[238:239], v[56:59], off offset:128
	v_pk_add_f32 v[52:53], v[52:53], v[204:205]
	v_pk_add_f32 v[54:55], v[54:55], v[206:207]
	global_store_dwordx4 v[238:239], v[52:55], off offset:192
	s_and_b64 vcc, exec, s[42:43]
	s_cbranch_vccz .Lmy_res_now_4
	v_pk_mul_f32 v[234:235], v[66:67], v[210:211]
	s_nop 0
	v_cvt_pk_bf16_f32 v225, v234, v235
	v_pk_mul_f32 v[234:235], v[64:65], v[208:209]
	v_pk_mul_f32 v[208:209], v[64:65], v[64:65]
	v_pk_mul_f32 v[210:211], v[66:67], v[66:67]
	v_add_f32_e32 v233, v208, v209
	v_add_f32_e32 v233, v233, v210
	v_cvt_pk_bf16_f32 v224, v234, v235
	v_add_f32_e32 v233, v233, v211
	v_add_f32_e32 v232, v232, v233
	v_pk_mul_f32 v[234:235], v[62:63], v[214:215]
	s_nop 0
	v_cvt_pk_bf16_f32 v227, v234, v235
	v_pk_mul_f32 v[234:235], v[60:61], v[212:213]
	v_pk_mul_f32 v[212:213], v[60:61], v[60:61]
	v_pk_mul_f32 v[214:215], v[62:63], v[62:63]
	v_add_f32_e32 v233, v212, v213
	v_add_f32_e32 v233, v233, v214
	v_cvt_pk_bf16_f32 v226, v234, v235
	v_add_f32_e32 v233, v233, v215
	v_add_f32_e32 v232, v232, v233
	s_nop 1
	v_permlane16_swap_b32_e32 v224, v226
	v_permlane16_swap_b32_e32 v225, v227
	v_pk_mul_f32 v[234:235], v[58:59], v[218:219]
	s_nop 0
	v_cvt_pk_bf16_f32 v229, v234, v235
	v_pk_mul_f32 v[234:235], v[56:57], v[216:217]
	v_pk_mul_f32 v[216:217], v[56:57], v[56:57]
	v_pk_mul_f32 v[218:219], v[58:59], v[58:59]
	v_add_f32_e32 v233, v216, v217
	v_add_f32_e32 v233, v233, v218
	v_cvt_pk_bf16_f32 v228, v234, v235
	v_add_f32_e32 v233, v233, v219
	v_add_f32_e32 v232, v232, v233
	v_pk_mul_f32 v[234:235], v[54:55], v[222:223]
	s_nop 0
	v_cvt_pk_bf16_f32 v231, v234, v235
	v_pk_mul_f32 v[234:235], v[52:53], v[220:221]
	v_pk_mul_f32 v[220:221], v[52:53], v[52:53]
	v_pk_mul_f32 v[222:223], v[54:55], v[54:55]
	v_add_f32_e32 v233, v220, v221
	v_add_f32_e32 v233, v233, v222
	v_cvt_pk_bf16_f32 v230, v234, v235
	v_add_f32_e32 v233, v233, v223
	v_add_f32_e32 v232, v232, v233
	s_nop 1
	v_permlane16_swap_b32_e32 v228, v230
	v_permlane16_swap_b32_e32 v229, v231
	v_mov_b32_e32 v192, v228
	v_mov_b32_e32 v193, v229
	v_mov_b32_e32 v194, v230
	v_mov_b32_e32 v195, v231
	v_mov_b32_dpp v228, v224 row_ror:8 row_mask:0xf bank_mask:0x3
	v_mov_b32_dpp v229, v225 row_ror:8 row_mask:0xf bank_mask:0x3
	v_mov_b32_dpp v230, v226 row_ror:8 row_mask:0xf bank_mask:0x3
	v_mov_b32_dpp v231, v227 row_ror:8 row_mask:0xf bank_mask:0x3
	v_mov_b32_dpp v224, v192 row_ror:8 row_mask:0xf bank_mask:0xc
	v_mov_b32_dpp v225, v193 row_ror:8 row_mask:0xf bank_mask:0xc
	v_mov_b32_dpp v226, v194 row_ror:8 row_mask:0xf bank_mask:0xc
	v_mov_b32_dpp v227, v195 row_ror:8 row_mask:0xf bank_mask:0xc
	global_store_dwordx4 v[188:189], v[224:227], off offset:32
	global_store_dwordx4 v[190:191], v[228:231], off offset:32
	s_nop 1
.Lmy_res_now_4:
	v_lshl_add_u64 v[238:239], v[242:243], 0, s[4:5]
	v_lshl_add_u64 v[236:237], v[240:241], 0, s[4:5]
	v_lshl_add_u64 v[236:237], v[236:237], 0, s[2:3]
	global_load_dwordx4 v[192:195], v[236:237], off offset:0
	global_load_dwordx4 v[196:199], v[236:237], off offset:64
	global_load_dwordx4 v[200:203], v[236:237], off offset:128
	global_load_dwordx4 v[204:207], v[236:237], off offset:192
	s_and_b64 vcc, exec, s[42:43]
	s_cbranch_vccz .Lmy_res_now_ld_6
	global_load_dwordx4 v[208:211], v[244:245], off offset:0
	global_load_dwordx4 v[212:215], v[244:245], off offset:64
	global_load_dwordx4 v[216:219], v[244:245], off offset:128
	global_load_dwordx4 v[220:223], v[244:245], off offset:192

; __device__ __forceinline__ void gemm_phase(const Ctx& cx, const GemmArgs& g_, char* shm) {
;     ...
;             } else if (g.epi == EPI_RES) {
;               const float4 hv = *(const float4*)(g.hin + (size_t)tok * DM + n0);
;               const float h0 = hv.x + a[0], h1 = hv.y + a[1], h2 = hv.z + a[2], h3 = hv.w + a[3];
;               *(float4*)(g.hout + (size_t)tok * DM + n0) = make_float4(h0, h1, h2, h3);
;               if (g.w != nullptr) {
;                 const float4 nw = *(const float4*)(g.w + n0);
;                 uint2 o; o.x = pack2(h0 * nw.x, h1 * nw.y); o.y = pack2(h2 * nw.z, h3 * nw.w);
;                 EMIT_BF16(DM, o);
;                 ssq += h0 * h0 + h1 * h1 + h2 * h2 + h3 * h3;
;               }
.Lmy_res_wj_5:
	v_pk_add_f32 v[48:49], v[48:49], v[100:101]
	v_pk_add_f32 v[50:51], v[50:51], v[102:103]
	global_store_dwordx4 v[238:239], v[48:51], off offset:512
	v_pk_add_f32 v[44:45], v[44:45], v[104:105]
	v_pk_add_f32 v[46:47], v[46:47], v[106:107]
	global_store_dwordx4 v[238:239], v[44:47], off offset:576
	v_pk_add_f32 v[40:41], v[40:41], v[108:109]
	v_pk_add_f32 v[42:43], v[42:43], v[110:111]
	global_store_dwordx4 v[238:239], v[40:43], off offset:640
	v_pk_add_f32 v[36:37], v[36:37], v[112:113]
	v_pk_add_f32 v[38:39], v[38:39], v[114:115]
	global_store_dwordx4 v[238:239], v[36:39], off offset:704
	s_and_b64 vcc, exec, s[42:43]
	s_cbranch_vccz .Lmy_res_now_5
	v_pk_mul_f32 v[234:235], v[50:51], v[118:119]
	s_nop 0
	v_cvt_pk_bf16_f32 v225, v234, v235
	v_pk_mul_f32 v[234:235], v[48:49], v[116:117]
	v_pk_mul_f32 v[116:117], v[48:49], v[48:49]
	v_pk_mul_f32 v[118:119], v[50:51], v[50:51]
	v_add_f32_e32 v233, v116, v117
	v_add_f32_e32 v233, v233, v118
	v_cvt_pk_bf16_f32 v224, v234, v235
	v_add_f32_e32 v233, v233, v119
	v_add_f32_e32 v232, v232, v233
	v_pk_mul_f32 v[234:235], v[46:47], v[122:123]
	s_nop 0
	v_cvt_pk_bf16_f32 v227, v234, v235
	v_pk_mul_f32 v[234:235], v[44:45], v[120:121]
	v_pk_mul_f32 v[120:121], v[44:45], v[44:45]
	v_pk_mul_f32 v[122:123], v[46:47], v[46:47]
	v_add_f32_e32 v233, v120, v121
	v_add_f32_e32 v233, v233, v122
	v_cvt_pk_bf16_f32 v226, v234, v235
	v_add_f32_e32 v233, v233, v123
	v_add_f32_e32 v232, v232, v233
	s_nop 1
	v_permlane16_swap_b32_e32 v224, v226
	v_permlane16_swap_b32_e32 v225, v227
	v_pk_mul_f32 v[234:235], v[42:43], v[126:127]
	s_nop 0
	v_cvt_pk_bf16_f32 v229, v234, v235
	v_pk_mul_f32 v[234:235], v[40:41], v[124:125]
	v_pk_mul_f32 v[124:125], v[40:41], v[40:41]
	v_pk_mul_f32 v[126:127], v[42:43], v[42:43]
	v_add_f32_e32 v233, v124, v125
	v_add_f32_e32 v233, v233, v126
	v_cvt_pk_bf16_f32 v228, v234, v235
	v_add_f32_e32 v233, v233, v127
	v_add_f32_e32 v232, v232, v233
	v_pk_mul_f32 v[234:235], v[38:39], v[130:131]
	s_nop 0
	v_cvt_pk_bf16_f32 v231, v234, v235
	v_pk_mul_f32 v[234:235], v[36:37], v[128:129]
	v_pk_mul_f32 v[128:129], v[36:37], v[36:37]
	v_pk_mul_f32 v[130:131], v[38:39], v[38:39]
	v_add_f32_e32 v233, v128, v129
	v_add_f32_e32 v233, v233, v130
	v_cvt_pk_bf16_f32 v230, v234, v235
	v_add_f32_e32 v233, v233, v131
	v_add_f32_e32 v232, v232, v233
	s_nop 1
	v_permlane16_swap_b32_e32 v228, v230
	v_permlane16_swap_b32_e32 v229, v231
	v_mov_b32_e32 v100, v228
	v_mov_b32_e32 v101, v229
	v_mov_b32_e32 v102, v230
	v_mov_b32_e32 v103, v231
	v_mov_b32_dpp v228, v224 row_ror:8 row_mask:0xf bank_mask:0x3
	v_mov_b32_dpp v229, v225 row_ror:8 row_mask:0xf bank_mask:0x3
	v_mov_b32_dpp v230, v226 row_ror:8 row_mask:0xf bank_mask:0x3
	v_mov_b32_dpp v231, v227 row_ror:8 row_mask:0xf bank_mask:0x3
	v_mov_b32_dpp v224, v100 row_ror:8 row_mask:0xf bank_mask:0xc
	v_mov_b32_dpp v225, v101 row_ror:8 row_mask:0xf bank_mask:0xc
	v_mov_b32_dpp v226, v102 row_ror:8 row_mask:0xf bank_mask:0xc
	v_mov_b32_dpp v227, v103 row_ror:8 row_mask:0xf bank_mask:0xc
	global_store_dwordx4 v[188:189], v[224:227], off offset:288
	global_store_dwordx4 v[190:191], v[228:231], off offset:288
	s_nop 1

; __device__ __forceinline__ void gemm_phase(const Ctx& cx, const GemmArgs& g_, char* shm) {
;     ...
;     for (int bj = 0; bj < 2; ++bj)
; #pragma unroll
;       for (int n = 0; n < 2; ++n) {
;         const int tok = bcol + bj * 128 + wc * 32 + n * 16 + fr;
;         float ssq = 0.f;
;         float rs = 1.f;
;         if ((g.epi == EPI_PROJ || g.epi == EPI_RELU2) && g.gate != nullptr)
;           rs = rsqrtf(((const float*)g.gate)[tok] * (1.0f / DM) + 1e-6f);
; #pragma unroll
;         for (int ai = 0; ai < 2; ++ai) {
;           uint2 pend = make_uint2(0u, 0u);
;     ...
;             } else if (g.epi == EPI_RES) {
;               const float4 hv = *(const float4*)(g.hin + (size_t)tok * DM + n0);
;               const float h0 = hv.x + a[0], h1 = hv.y + a[1], h2 = hv.z + a[2], h3 = hv.w + a[3];
;               *(float4*)(g.hout + (size_t)tok * DM + n0) = make_float4(h0, h1, h2, h3);
;               if (g.w != nullptr) {
;                 const float4 nw = *(const float4*)(g.w + n0);
.Lmy_res_noat_2:
	v_lshl_add_u64 v[188:189], v[184:185], 0, s[10:11]
	v_lshl_add_u64 v[188:189], v[188:189], 0, s[8:9]
	v_lshl_add_u64 v[190:191], v[188:189], 0, s[6:7]
	v_mov_b32_e32 v232, 0
	v_lshl_add_u64 v[238:239], v[242:243], 0, s[4:5]
	v_lshl_add_u64 v[238:239], v[238:239], 0, s[2:3]
	v_lshl_add_u64 v[236:237], v[240:241], 0, s[4:5]
	v_lshl_add_u64 v[236:237], v[236:237], 0, s[2:3]
	global_load_dwordx4 v[100:103], v[236:237], off offset:512
	global_load_dwordx4 v[104:107], v[236:237], off offset:576
	global_load_dwordx4 v[108:111], v[236:237], off offset:640
	global_load_dwordx4 v[112:115], v[236:237], off offset:704
	s_and_b64 vcc, exec, s[42:43]
	s_cbranch_vccz .Lmy_res_now_ld_7
	global_load_dwordx4 v[116:119], v[244:245], off offset:512
	global_load_dwordx4 v[120:123], v[244:245], off offset:576
	global_load_dwordx4 v[124:127], v[244:245], off offset:640
	global_load_dwordx4 v[128:131], v[244:245], off offset:704

; __device__ __forceinline__ void gemm_phase(const Ctx& cx, const GemmArgs& g_, char* shm) {
;     ...
;             } else if (g.epi == EPI_RES) {
;               const float4 hv = *(const float4*)(g.hin + (size_t)tok * DM + n0);
;               const float h0 = hv.x + a[0], h1 = hv.y + a[1], h2 = hv.z + a[2], h3 = hv.w + a[3];
;               *(float4*)(g.hout + (size_t)tok * DM + n0) = make_float4(h0, h1, h2, h3);
;               if (g.w != nullptr) {
;                 const float4 nw = *(const float4*)(g.w + n0);
;                 uint2 o; o.x = pack2(h0 * nw.x, h1 * nw.y); o.y = pack2(h2 * nw.z, h3 * nw.w);
;                 EMIT_BF16(DM, o);
;                 ssq += h0 * h0 + h1 * h1 + h2 * h2 + h3 * h3;
;               }
.Lmy_res_wj_6:
	v_pk_add_f32 v[32:33], v[32:33], v[192:193]
	v_pk_add_f32 v[34:35], v[34:35], v[194:195]
	global_store_dwordx4 v[238:239], v[32:35], off offset:0
	v_pk_add_f32 v[28:29], v[28:29], v[196:197]
	v_pk_add_f32 v[30:31], v[30:31], v[198:199]
	global_store_dwordx4 v[238:239], v[28:31], off offset:64
	v_pk_add_f32 v[24:25], v[24:25], v[200:201]
	v_pk_add_f32 v[26:27], v[26:27], v[202:203]
	global_store_dwordx4 v[238:239], v[24:27], off offset:128
	v_pk_add_f32 v[20:21], v[20:21], v[204:205]
	v_pk_add_f32 v[22:23], v[22:23], v[206:207]
	global_store_dwordx4 v[238:239], v[20:23], off offset:192
	s_and_b64 vcc, exec, s[42:43]
	s_cbranch_vccz .Lmy_res_now_6
	v_pk_mul_f32 v[234:235], v[34:35], v[210:211]
	s_nop 0
	v_cvt_pk_bf16_f32 v225, v234, v235
	v_pk_mul_f32 v[234:235], v[32:33], v[208:209]
	v_pk_mul_f32 v[208:209], v[32:33], v[32:33]
	v_pk_mul_f32 v[210:211], v[34:35], v[34:35]
	v_add_f32_e32 v233, v208, v209
	v_add_f32_e32 v233, v233, v210
	v_cvt_pk_bf16_f32 v224, v234, v235
	v_add_f32_e32 v233, v233, v211
	v_add_f32_e32 v232, v232, v233
	v_pk_mul_f32 v[234:235], v[30:31], v[214:215]
	s_nop 0
	v_cvt_pk_bf16_f32 v227, v234, v235
	v_pk_mul_f32 v[234:235], v[28:29], v[212:213]
	v_pk_mul_f32 v[212:213], v[28:29], v[28:29]
	v_pk_mul_f32 v[214:215], v[30:31], v[30:31]
	v_add_f32_e32 v233, v212, v213
	v_add_f32_e32 v233, v233, v214
	v_cvt_pk_bf16_f32 v226, v234, v235
	v_add_f32_e32 v233, v233, v215
	v_add_f32_e32 v232, v232, v233
	s_nop 1
	v_permlane16_swap_b32_e32 v224, v226
	v_permlane16_swap_b32_e32 v225, v227
	v_pk_mul_f32 v[234:235], v[26:27], v[218:219]
	s_nop 0
	v_cvt_pk_bf16_f32 v229, v234, v235
	v_pk_mul_f32 v[234:235], v[24:25], v[216:217]
	v_pk_mul_f32 v[216:217], v[24:25], v[24:25]
	v_pk_mul_f32 v[218:219], v[26:27], v[26:27]
	v_add_f32_e32 v233, v216, v217
	v_add_f32_e32 v233, v233, v218
	v_cvt_pk_bf16_f32 v228, v234, v235
	v_add_f32_e32 v233, v233, v219
	v_add_f32_e32 v232, v232, v233
	v_pk_mul_f32 v[234:235], v[22:23], v[222:223]
	s_nop 0
	v_cvt_pk_bf16_f32 v231, v234, v235
	v_pk_mul_f32 v[234:235], v[20:21], v[220:221]
	v_pk_mul_f32 v[220:221], v[20:21], v[20:21]
	v_pk_mul_f32 v[222:223], v[22:23], v[22:23]
	v_add_f32_e32 v233, v220, v221
	v_add_f32_e32 v233, v233, v222
	v_cvt_pk_bf16_f32 v230, v234, v235
	v_add_f32_e32 v233, v233, v223
	v_add_f32_e32 v232, v232, v233
	s_nop 1
	v_permlane16_swap_b32_e32 v228, v230
	v_permlane16_swap_b32_e32 v229, v231
	v_mov_b32_e32 v192, v228
	v_mov_b32_e32 v193, v229
	v_mov_b32_e32 v194, v230
	v_mov_b32_e32 v195, v231
	v_mov_b32_dpp v228, v224 row_ror:8 row_mask:0xf bank_mask:0x3
	v_mov_b32_dpp v229, v225 row_ror:8 row_mask:0xf bank_mask:0x3
	v_mov_b32_dpp v230, v226 row_ror:8 row_mask:0xf bank_mask:0x3
	v_mov_b32_dpp v231, v227 row_ror:8 row_mask:0xf bank_mask:0x3
	v_mov_b32_dpp v224, v192 row_ror:8 row_mask:0xf bank_mask:0xc
	v_mov_b32_dpp v225, v193 row_ror:8 row_mask:0xf bank_mask:0xc
	v_mov_b32_dpp v226, v194 row_ror:8 row_mask:0xf bank_mask:0xc
	v_mov_b32_dpp v227, v195 row_ror:8 row_mask:0xf bank_mask:0xc
	global_store_dwordx4 v[188:189], v[224:227], off offset:32
	global_store_dwordx4 v[190:191], v[228:231], off offset:32
	s_nop 1
.Lmy_res_now_6:
	v_lshl_add_u64 v[238:239], v[242:243], 0, s[4:5]
	v_lshl_add_u64 v[238:239], v[238:239], 0, s[2:3]
	s_and_b64 vcc, exec, s[42:43]
	s_cbranch_vccz .Lmy_res_w0_7
	s_waitcnt vmcnt(6)
	s_branch .Lmy_res_wj_7

; __device__ __forceinline__ void gemm_phase(const Ctx& cx, const GemmArgs& g_, char* shm) {
;     ...
;             } else if (g.epi == EPI_RES) {
;               const float4 hv = *(const float4*)(g.hin + (size_t)tok * DM + n0);
;               const float h0 = hv.x + a[0], h1 = hv.y + a[1], h2 = hv.z + a[2], h3 = hv.w + a[3];
;               *(float4*)(g.hout + (size_t)tok * DM + n0) = make_float4(h0, h1, h2, h3);
;               if (g.w != nullptr) {
;                 const float4 nw = *(const float4*)(g.w + n0);
;                 uint2 o; o.x = pack2(h0 * nw.x, h1 * nw.y); o.y = pack2(h2 * nw.z, h3 * nw.w);
;                 EMIT_BF16(DM, o);
;                 ssq += h0 * h0 + h1 * h1 + h2 * h2 + h3 * h3;
;               }
.Lmy_res_wj_7:
	v_pk_add_f32 v[16:17], v[16:17], v[100:101]
	v_pk_add_f32 v[18:19], v[18:19], v[102:103]
	global_store_dwordx4 v[238:239], v[16:19], off offset:512
	v_pk_add_f32 v[12:13], v[12:13], v[104:105]
	v_pk_add_f32 v[14:15], v[14:15], v[106:107]
	global_store_dwordx4 v[238:239], v[12:15], off offset:576
	v_pk_add_f32 v[8:9], v[8:9], v[108:109]
	v_pk_add_f32 v[10:11], v[10:11], v[110:111]
	global_store_dwordx4 v[238:239], v[8:11], off offset:640
	v_pk_add_f32 v[4:5], v[4:5], v[112:113]
	v_pk_add_f32 v[6:7], v[6:7], v[114:115]
	global_store_dwordx4 v[238:239], v[4:7], off offset:704
	s_and_b64 vcc, exec, s[42:43]
	s_cbranch_vccz .Lmy_res_now_7
	v_pk_mul_f32 v[234:235], v[18:19], v[118:119]
	s_nop 0
	v_cvt_pk_bf16_f32 v225, v234, v235
	v_pk_mul_f32 v[234:235], v[16:17], v[116:117]
	v_pk_mul_f32 v[116:117], v[16:17], v[16:17]
	v_pk_mul_f32 v[118:119], v[18:19], v[18:19]
	v_add_f32_e32 v233, v116, v117
	v_add_f32_e32 v233, v233, v118
	v_cvt_pk_bf16_f32 v224, v234, v235
	v_add_f32_e32 v233, v233, v119
	v_add_f32_e32 v232, v232, v233
	v_pk_mul_f32 v[234:235], v[14:15], v[122:123]
	s_nop 0
	v_cvt_pk_bf16_f32 v227, v234, v235
	v_pk_mul_f32 v[234:235], v[12:13], v[120:121]
	v_pk_mul_f32 v[120:121], v[12:13], v[12:13]
	v_pk_mul_f32 v[122:123], v[14:15], v[14:15]
	v_add_f32_e32 v233, v120, v121
	v_add_f32_e32 v233, v233, v122
	v_cvt_pk_bf16_f32 v226, v234, v235
	v_add_f32_e32 v233, v233, v123
	v_add_f32_e32 v232, v232, v233
	s_nop 1
	v_permlane16_swap_b32_e32 v224, v226
	v_permlane16_swap_b32_e32 v225, v227
	v_pk_mul_f32 v[234:235], v[10:11], v[126:127]
	s_nop 0
	v_cvt_pk_bf16_f32 v229, v234, v235
	v_pk_mul_f32 v[234:235], v[8:9], v[124:125]
	v_pk_mul_f32 v[124:125], v[8:9], v[8:9]
	v_pk_mul_f32 v[126:127], v[10:11], v[10:11]
	v_add_f32_e32 v233, v124, v125
	v_add_f32_e32 v233, v233, v126
	v_cvt_pk_bf16_f32 v228, v234, v235
	v_add_f32_e32 v233, v233, v127
	v_add_f32_e32 v232, v232, v233
	v_pk_mul_f32 v[234:235], v[6:7], v[130:131]
	s_nop 0
	v_cvt_pk_bf16_f32 v231, v234, v235
	v_pk_mul_f32 v[234:235], v[4:5], v[128:129]
	v_pk_mul_f32 v[128:129], v[4:5], v[4:5]
	v_pk_mul_f32 v[130:131], v[6:7], v[6:7]
	v_add_f32_e32 v233, v128, v129
	v_add_f32_e32 v233, v233, v130
	v_cvt_pk_bf16_f32 v230, v234, v235
	v_add_f32_e32 v233, v233, v131
	v_add_f32_e32 v232, v232, v233
	s_nop 1
	v_permlane16_swap_b32_e32 v228, v230
	v_permlane16_swap_b32_e32 v229, v231
	v_mov_b32_e32 v100, v228
	v_mov_b32_e32 v101, v229
	v_mov_b32_e32 v102, v230
	v_mov_b32_e32 v103, v231
	v_mov_b32_dpp v228, v224 row_ror:8 row_mask:0xf bank_mask:0x3
	v_mov_b32_dpp v229, v225 row_ror:8 row_mask:0xf bank_mask:0x3
	v_mov_b32_dpp v230, v226 row_ror:8 row_mask:0xf bank_mask:0x3
	v_mov_b32_dpp v231, v227 row_ror:8 row_mask:0xf bank_mask:0x3
	v_mov_b32_dpp v224, v100 row_ror:8 row_mask:0xf bank_mask:0xc
	v_mov_b32_dpp v225, v101 row_ror:8 row_mask:0xf bank_mask:0xc
	v_mov_b32_dpp v226, v102 row_ror:8 row_mask:0xf bank_mask:0xc
	v_mov_b32_dpp v227, v103 row_ror:8 row_mask:0xf bank_mask:0xc
	global_store_dwordx4 v[188:189], v[224:227], off offset:288
	global_store_dwordx4 v[190:191], v[228:231], off offset:288
	s_nop 1
